# SWA prompt q-tile: RoPE operand loads and both halves of the q row issued together at the top of the q-tile (one exposed round trip instead of three)
# baseline (speedup 1.0000x reference)
; __device__ __forceinline__ unsigned cvt_pk_bf16(float lo, float hi) { unsigned r; asm volatile("v_cvt_pk_bf16_f32 %0, %1, %2" : "=v"(r) : "v"(lo), "v"(hi)); return r; }
; __device__ __forceinline__ float bflo(unsigned w) { return __uint_as_float(w << 16); }
; __device__ __forceinline__ float bfhi(unsigned w) { return __uint_as_float(w & 0xffff0000u); }
; __device__ __forceinline__ void swa_prompt_unit(const Args& a, unsigned char* lds, int unit, int tid) {
;     ...
;         const int q0 = (wave & 1) * 64 + qt * 16, qi = q0 + r16, qpos = blk * 128 + qi; const size_t row = (size_t)b * 2048 + qpos;
;         bf16x8 qf[2];
; #pragma unroll
;         for (int kk = 0; kk < 2; ++kk) { const int c = kk * 4 + q4; const bf16_t* qp = Z + row * DINP + ZQS + (kvh * 4 + g) * 64;
;             const u32x4 raw = *(const u32x4*)(qp + c * 8); float f[8];
;             f[0] = bflo(raw.x); f[1] = bfhi(raw.x); f[2] = bflo(raw.y); f[3] = bfhi(raw.y); f[4] = bflo(raw.z); f[5] = bfhi(raw.z); f[6] = bflo(raw.w); f[7] = bfhi(raw.w);
;             if (kk == 0 && q4 < 2) { const u32x4 pr = *(const u32x4*)(qp + (c ^ 1) * 8);
;                 float pf[8]; pf[0] = bflo(pr.x); pf[1] = bfhi(pr.x); pf[2] = bflo(pr.y); pf[3] = bfhi(pr.y); pf[4] = bflo(pr.z); pf[5] = bfhi(pr.z); pf[6] = bflo(pr.w); pf[7] = bfhi(pr.w);
;                 const f32x2* rp = ROPE + qpos * 8; const float sg = c == 0 ? -1.f : 1.f;
; #pragma unroll
;                 for (int d = 0; d < 8; ++d) { const f32x2 cs = rp[d]; f[d] = f[d] * cs.x + sg * pf[d] * cs.y; } }
;             u32x4 w; w.x = cvt_pk_bf16(f[0] * 0.125f, f[1] * 0.125f); w.y = cvt_pk_bf16(f[2] * 0.125f, f[3] * 0.125f); w.z = cvt_pk_bf16(f[4] * 0.125f, f[5] * 0.125f); w.w = cvt_pk_bf16(f[6] * 0.125f, f[7] * 0.125f);
;             asm volatile("s_nop 4" : "+v"(w));
;             qf[kk] = __builtin_bit_cast(bf16x8, w); }
.LBB0_281:
	s_and_saveexec_b64 s[0:1], s[12:13]
	v_lshl_add_u64 v[20:21], s[86:87], 0, v[98:99]
	global_load_dwordx4 v[20:23], v[20:21], off
	v_lshl_add_u64 v[28:29], s[86:87], 0, v[96:97]
	s_mov_b64 s[18:19], 0xa0000
	s_mov_b32 s20, 0xa0000
	v_lshl_add_u64 v[36:37], v[28:29], 0, s[18:19]
	v_add_co_u32_e32 v28, vcc, s20, v28
	global_load_dwordx4 v[24:27], v[36:37], off offset:48
	s_nop 0
	v_addc_co_u32_e32 v29, vcc, 0, v29, vcc
	global_load_dwordx4 v[28:31], v[28:29], off
	s_nop 0
	global_load_dwordx4 v[32:35], v[36:37], off offset:16
	s_nop 0
	global_load_dwordx4 v[36:39], v[36:37], off offset:32
	s_or_b64 exec, exec, s[0:1]
	v_lshl_add_u64 v[2:3], s[86:87], 0, v[102:103]
	v_add_co_u32_e32 v4, vcc, 0xc600000, v2
	s_nop 1
	v_addc_co_u32_e32 v5, vcc, 0, v3, vcc
	global_load_dwordx4 v[16:19], v[4:5], off
	global_load_dwordx4 v[252:255], v[4:5], off offset:64
	s_waitcnt vmcnt(1)
	v_lshlrev_b32_e32 v14, 16, v16
	v_and_b32_e32 v12, 0xffff0000, v16
	v_lshlrev_b32_e32 v10, 16, v17
	v_and_b32_e32 v8, 0xffff0000, v17
	v_lshlrev_b32_e32 v6, 16, v18
	v_and_b32_e32 v4, 0xffff0000, v18
	v_lshlrev_b32_e32 v16, 16, v19
	v_and_b32_e32 v18, 0xffff0000, v19
	s_and_saveexec_b64 s[0:1], s[12:13]
	s_cbranch_execz .LBB0_283
	s_waitcnt vmcnt(4)
	v_and_b32_e32 v5, 0xffff0000, v20
	v_lshlrev_b32_e32 v7, 16, v21
	v_and_b32_e32 v9, 0xffff0000, v21
	v_and_b32_e32 v19, 0xffff0000, v22
	v_and_b32_e32 v21, 0xffff0000, v23
	v_lshlrev_b32_e32 v1, 16, v20
	v_lshlrev_b32_e32 v20, 16, v23
	v_cndmask_b32_e64 v13, v5, -v5, s[14:15]
	v_cndmask_b32_e64 v5, v19, -v19, s[14:15]
	v_cndmask_b32_e64 v19, v21, -v21, s[14:15]
	v_lshlrev_b32_e32 v17, 16, v22
	v_cndmask_b32_e64 v15, v1, -v1, s[14:15]
	v_cndmask_b32_e64 v1, v20, -v20, s[14:15]
	s_waitcnt vmcnt(3)
	v_pk_mul_f32 v[18:19], v[26:27], v[18:19]
	v_cndmask_b32_e64 v11, v7, -v7, s[14:15]
	v_cndmask_b32_e64 v9, v9, -v9, s[14:15]
	v_cndmask_b32_e64 v7, v17, -v17, s[14:15]
	v_mul_f32_e32 v16, v24, v16
	s_waitcnt vmcnt(2)
	v_mul_f32_e32 v20, v30, v12
	v_mul_f32_e32 v42, v1, v25
	v_mov_b32_e32 v17, v18
	v_mov_b32_e32 v43, v19
	v_pk_mul_f32 v[14:15], v[28:29], v[14:15]
	s_waitcnt vmcnt(1)
	v_mul_f32_e32 v22, v33, v11
	v_mul_f32_e32 v24, v35, v9
	s_waitcnt vmcnt(0)
	v_mul_f32_e32 v28, v37, v7
	v_mul_f32_e32 v40, v39, v5
	v_pk_fma_f32 v[12:13], v[30:31], v[12:13], v[20:21] op_sel_hi:[1,1,0]
	v_pk_add_f32 v[16:17], v[16:17], v[42:43]
	v_pk_fma_f32 v[10:11], v[32:33], v[10:11], v[22:23] op_sel_hi:[1,1,0]
	v_pk_fma_f32 v[8:9], v[34:35], v[8:9], v[24:25] op_sel_hi:[1,1,0]
	v_pk_fma_f32 v[6:7], v[36:37], v[6:7], v[28:29] op_sel_hi:[1,1,0]
	v_pk_fma_f32 v[4:5], v[38:39], v[4:5], v[40:41] op_sel_hi:[1,1,0]
	v_add_f32_e32 v14, v14, v15
	v_mov_b32_e32 v12, v13
	v_mov_b32_e32 v18, v17
.LBB0_283:
	s_or_b64 exec, exec, s[0:1]
	v_mul_f32_e32 v1, 0x3e000000, v14
	v_mul_f32_e32 v5, 0x3e000000, v12
	v_cvt_pk_bf16_f32 v66, v1, v5
	v_mul_f32_e32 v1, 0x3e000000, v10
	v_mul_f32_e32 v5, 0x3e000000, v8
	v_cvt_pk_bf16_f32 v67, v1, v5
	v_mul_f32_e32 v1, 0x3e000000, v6
	v_mul_f32_e32 v4, 0x3e000000, v4
	v_add_co_u32_e32 v2, vcc, s3, v2
	v_cvt_pk_bf16_f32 v68, v1, v4
	v_mul_f32_e32 v1, 0x3e000000, v16
	v_mul_f32_e32 v4, 0x3e000000, v18
	v_cvt_pk_bf16_f32 v69, v1, v4
	v_addc_co_u32_e32 v3, vcc, 0, v3, vcc
	s_nop 4
	v_add_u32_e32 v1, s62, v107
	v_mov_b32_e32 v54, 0
	v_mov_b32_e32 v62, 0
	v_mov_b32_e32 v63, 0
	v_mov_b32_e32 v64, 0
	v_cmp_ne_u32_e32 vcc, 0, v1
	v_cmp_eq_u32_e64 s[44:45], 0, v1
	v_mov_b32_e32 v65, 0
	s_waitcnt vmcnt(0)
	v_lshlrev_b32_e32 v6, 16, v252
	v_and_b32_e32 v2, 0xffff0000, v252
	v_lshlrev_b32_e32 v7, 16, v253
	v_and_b32_e32 v3, 0xffff0000, v253
	v_lshlrev_b32_e32 v8, 16, v254
	v_and_b32_e32 v4, 0xffff0000, v254
	v_lshlrev_b32_e32 v9, 16, v255
	v_and_b32_e32 v5, 0xffff0000, v255
	v_mul_f32_e32 v6, 0x3e000000, v6
	v_mul_f32_e32 v2, 0x3e000000, v2
	v_mul_f32_e32 v7, 0x3e000000, v7
	v_mul_f32_e32 v3, 0x3e000000, v3
	v_mul_f32_e32 v8, 0x3e000000, v8
	v_mul_f32_e32 v4, 0x3e000000, v4
	v_mul_f32_e32 v9, 0x3e000000, v9
	v_mul_f32_e32 v5, 0x3e000000, v5
	v_cvt_pk_bf16_f32 v70, v6, v2
	v_cvt_pk_bf16_f32 v71, v7, v3
	v_cvt_pk_bf16_f32 v72, v8, v4
	v_cvt_pk_bf16_f32 v73, v9, v5
	s_nop 0
	s_nop 4
	s_and_saveexec_b64 s[0:1], s[44:45]
	s_cbranch_execz .LBB0_285
	ds_read_b128 v[2:5], v187
	ds_read_b128 v[6:9], v187 offset:64
	s_waitcnt lgkmcnt(1)
	v_mfma_f32_16x16x32_bf16 v[2:5], v[2:5], v[66:69], 0
	s_waitcnt lgkmcnt(0)
	v_mfma_f32_16x16x32_bf16 v[62:65], v[6:9], v[70:73], v[2:5]
